# plus ssd_passA/passC: conditional previous-token loads no longer waited one by one inside their predicated blocks (loaded to private temporaries, converted once before first use)
# speedup vs baseline: 1.0195x; 1.0195x over previous
.LBB0_70:
	s_cmpk_lt_i32 s50, 0x200
	s_mov_b64 s[4:5], -1
	s_cbranch_scc1 .LBB0_106
	s_add_i32 s2, s50, 0xfffffe00
	s_lshr_b32 s37, s2, 7
	s_bfe_u32 s40, s50, 0x60001
	s_lshl_b32 s2, s37, 13
	s_lshl_b32 s3, s40, 7
	s_or_b32 s41, s3, s2
	s_mov_b32 s2, 14
	s_and_b32 s42, s50, 1
	s_sub_i32 s43, 0, s3
	s_ashr_i32 s3, s2, 31
	s_lshl_b32 s45, s42, 7
	s_add_i32 s44, s41, -3
	s_lshl_b64 s[2:3], s[2:3], 3
	v_readlane_b32 s20, v254, 53
	s_add_u32 s2, s0, s2
	s_mov_b32 s4, 15
	s_mov_b32 s6, 16
	s_mov_b32 s10, 17
	v_mov_b32_e32 v2, v183
	v_mov_b32_e32 v36, v1
	v_mov_b32_e32 v0, s20
	s_addc_u32 s3, s1, s3
	s_ashr_i32 s5, s4, 31
	s_waitcnt lgkmcnt(0)
	s_barrier
	v_ashrrev_i32_e32 v3, 31, v2
	s_lshl_b64 s[4:5], s[4:5], 3
	v_add_u32_sdwa v0, v2, v3 dst_sel:DWORD dst_unused:UNUSED_PAD src0_sel:DWORD src1_sel:BYTE_3
	s_add_u32 s4, s0, s4
	v_ashrrev_i32_e32 v91, 8, v0
	s_addc_u32 s5, s1, s5
	s_ashr_i32 s7, s6, 31
	v_mul_i32_i24_e32 v0, 0x100, v91
	s_lshl_b64 s[6:7], s[6:7], 3
	v_sub_u32_e32 v15, v2, v0
	s_add_u32 s6, s0, s6
	v_lshlrev_b32_e32 v18, 1, v15
	s_addc_u32 s7, s1, s7
	s_ashr_i32 s11, s10, 31
	v_readlane_b32 s20, v254, 54
	v_and_b32_e32 v92, 0x7f, v15
	v_and_b32_e32 v0, 0xffffff00, v18
	v_lshlrev_b32_e32 v67, 5, v91
	s_lshl_b64 s[10:11], s[10:11], 3
	v_mov_b32_e32 v37, s20
	v_readlane_b32 s20, v254, 55
	v_or3_b32 v10, s45, v0, v92
	v_add_u32_e32 v0, s44, v67
	v_mov_b64_e32 v[4:5], s[26:27]
	s_add_u32 s10, s0, s10
	v_mov_b32_e32 v38, s20
	v_mad_i64_i32 v[4:5], s[20:21], v0, s18, v[4:5]
	v_ashrrev_i32_e32 v11, 31, v10
	s_addc_u32 s11, s1, s11
	v_readfirstlane_b32 s36, v2
	v_lshl_add_u64 v[4:5], v[10:11], 1, v[4:5]
	v_cmp_lt_i32_e64 s[38:39], s43, v67
	v_mov_b32_e32 v19, 0
	v_mov_b32_e32 v20, 0
	v_mov_b32_e32 v21, 0
	v_mov_b32_e32 v228, 0
	v_mov_b32_e32 v229, 0
	s_and_saveexec_b64 s[20:21], s[38:39]
	s_mov_b32 s48, 0x3f2aaaab
	s_mov_b32 s49, 0x3f317218
	s_mov_b32 s60, 0x33800000
	s_cbranch_execz .LBB0_73
	v_add_co_u32_e32 v6, vcc, 0x2000, v4
	s_nop 1
	v_addc_co_u32_e32 v7, vcc, 0, v5, vcc
	flat_load_ushort v228, v[6:7] offset:3584
	v_add_co_u32_e32 v6, vcc, 0x1000, v4
	s_nop 0
	s_nop 0
	v_addc_co_u32_e32 v7, vcc, 0, v5, vcc
	flat_load_ushort v229, v[6:7]
	s_nop 0
	s_nop 0
.LBB0_73:
	s_or_b64 exec, exec, s[20:21]
	s_load_dwordx2 s[52:53], s[2:3], 0x0
	s_load_dwordx2 s[20:21], s[4:5], 0x0
	s_load_dwordx2 s[56:57], s[6:7], 0x0
	s_load_dwordx2 s[58:59], s[10:11], 0x0
	v_mov_b32_e32 v230, 0
	s_and_saveexec_b64 s[2:3], s[38:39]
	s_cbranch_execz .LBB0_75
	v_add_co_u32_e32 v6, vcc, 0x4000, v4
	s_nop 1
	v_addc_co_u32_e32 v7, vcc, 0, v5, vcc
	flat_load_ushort v230, v[6:7] offset:3072
	s_nop 0
	s_nop 0
.LBB0_75:
	s_or_b64 exec, exec, s[2:3]
	v_add_co_u32_e32 v6, vcc, 0x6000, v4
	s_mov_b32 s2, 0xc000
	s_nop 0
	v_addc_co_u32_e32 v7, vcc, 0, v5, vcc
	flat_load_ushort v22, v[6:7] offset:2560
	v_add_co_u32_e32 v6, vcc, 0x8000, v4
	v_add_u32_e32 v0, 0x200, v2
	s_nop 0
	v_addc_co_u32_e32 v7, vcc, 0, v5, vcc
	flat_load_ushort v26, v[6:7] offset:2048
	v_add_co_u32_e32 v6, vcc, 0xa000, v4
	s_nop 1
	v_addc_co_u32_e32 v7, vcc, 0, v5, vcc
	flat_load_ushort v27, v[6:7] offset:1536
	v_add_co_u32_e32 v6, vcc, s2, v4
	s_mov_b32 s2, 0x11000
	s_nop 0
	v_addc_co_u32_e32 v7, vcc, 0, v5, vcc
	flat_load_ushort v28, v[6:7] offset:1024
	v_add_co_u32_e32 v6, vcc, 0xe000, v4
	s_nop 1
	v_addc_co_u32_e32 v7, vcc, 0, v5, vcc
	flat_load_ushort v29, v[6:7] offset:512
	v_add_co_u32_e32 v6, vcc, s28, v4
	s_nop 1
	v_addc_co_u32_e32 v7, vcc, 0, v5, vcc
	flat_load_ushort v23, v[6:7]
	v_add_co_u32_e32 v6, vcc, s2, v4
	s_mov_b32 s2, 0x20000
	s_nop 0
	v_addc_co_u32_e32 v7, vcc, 0, v5, vcc
	flat_load_ushort v24, v[6:7] offset:3584
	v_add_co_u32_e32 v6, vcc, 0x13000, v4
	s_nop 1
	v_addc_co_u32_e32 v7, vcc, 0, v5, vcc
	flat_load_ushort v30, v[6:7] offset:3072
	v_add_co_u32_e32 v6, vcc, 0x15000, v4
	s_nop 1
	v_addc_co_u32_e32 v7, vcc, 0, v5, vcc
	flat_load_ushort v95, v[6:7] offset:2560
	v_add_co_u32_e32 v6, vcc, 0x17000, v4
	s_nop 1
	v_addc_co_u32_e32 v7, vcc, 0, v5, vcc
	flat_load_ushort v94, v[6:7] offset:2048
	v_add_co_u32_e32 v6, vcc, 0x19000, v4
	s_nop 1
	v_addc_co_u32_e32 v7, vcc, 0, v5, vcc
	flat_load_ushort v96, v[6:7] offset:1536
	v_add_co_u32_e32 v6, vcc, 0x1b000, v4
	s_nop 1
	v_addc_co_u32_e32 v7, vcc, 0, v5, vcc
	flat_load_ushort v97, v[6:7] offset:1024
	v_add_co_u32_e32 v6, vcc, 0x1d000, v4
	s_nop 1
	v_addc_co_u32_e32 v7, vcc, 0, v5, vcc
	flat_load_ushort v98, v[6:7] offset:512
	v_add_co_u32_e32 v6, vcc, 0x1f000, v4
	s_nop 1
	v_addc_co_u32_e32 v7, vcc, 0, v5, vcc
	flat_load_ushort v99, v[6:7]
	v_add_co_u32_e32 v6, vcc, s2, v4
	s_mov_b32 s2, 0x28000
	s_nop 0
	v_addc_co_u32_e32 v7, vcc, 0, v5, vcc
	flat_load_ushort v100, v[6:7] offset:3584
	v_add_co_u32_e32 v6, vcc, 0x22000, v4
	s_nop 1
	v_addc_co_u32_e32 v7, vcc, 0, v5, vcc
	flat_load_ushort v101, v[6:7] offset:3072
	v_add_co_u32_e32 v6, vcc, 0x24000, v4
	s_nop 1
	v_addc_co_u32_e32 v7, vcc, 0, v5, vcc
	flat_load_ushort v84, v[6:7] offset:2560
	v_add_co_u32_e32 v6, vcc, 0x26000, v4
	s_nop 1
	v_addc_co_u32_e32 v7, vcc, 0, v5, vcc
	flat_load_ushort v83, v[6:7] offset:2048
	v_add_co_u32_e32 v6, vcc, s2, v4
	s_nop 1
	v_addc_co_u32_e32 v7, vcc, 0, v5, vcc
	flat_load_ushort v85, v[6:7] offset:1536
	v_add_co_u32_e32 v6, vcc, 0x2a000, v4
	s_nop 1
	v_addc_co_u32_e32 v7, vcc, 0, v5, vcc
	flat_load_ushort v86, v[6:7] offset:1024
	v_add_co_u32_e32 v6, vcc, 0x2c000, v4
	s_nop 1
	v_addc_co_u32_e32 v7, vcc, 0, v5, vcc
	flat_load_ushort v87, v[6:7] offset:512
	v_add_co_u32_e32 v6, vcc, 0x2e000, v4
	s_nop 1
	v_addc_co_u32_e32 v7, vcc, 0, v5, vcc
	flat_load_ushort v88, v[6:7]
	v_add_co_u32_e32 v6, vcc, 0x2f000, v4
	s_nop 1
	v_addc_co_u32_e32 v7, vcc, 0, v5, vcc
	flat_load_ushort v89, v[6:7] offset:3584
	v_add_co_u32_e32 v6, vcc, 0x31000, v4
	s_nop 1
	v_addc_co_u32_e32 v7, vcc, 0, v5, vcc
	flat_load_ushort v90, v[6:7] offset:3072
	v_add_co_u32_e32 v6, vcc, 0x33000, v4
	s_nop 1
	v_addc_co_u32_e32 v7, vcc, 0, v5, vcc
	flat_load_ushort v35, v[6:7] offset:2560
	v_add_co_u32_e32 v6, vcc, 0x35000, v4
	s_nop 1
	v_addc_co_u32_e32 v7, vcc, 0, v5, vcc
	flat_load_ushort v34, v[6:7] offset:2048
	v_add_co_u32_e32 v6, vcc, 0x37000, v4
	s_nop 1
	v_addc_co_u32_e32 v7, vcc, 0, v5, vcc
	flat_load_ushort v77, v[6:7] offset:1536
	v_add_co_u32_e32 v6, vcc, 0x39000, v4
	s_nop 1
	v_addc_co_u32_e32 v7, vcc, 0, v5, vcc
	flat_load_ushort v78, v[6:7] offset:1024
	v_add_co_u32_e32 v6, vcc, 0x3b000, v4
	s_nop 1
	v_addc_co_u32_e32 v7, vcc, 0, v5, vcc
	flat_load_ushort v79, v[6:7] offset:512
	v_add_co_u32_e32 v6, vcc, 0x3d000, v4
	s_nop 1
	v_addc_co_u32_e32 v7, vcc, 0, v5, vcc
	flat_load_ushort v80, v[6:7]
	v_add_co_u32_e32 v6, vcc, 0x3e000, v4
	s_nop 1
	v_addc_co_u32_e32 v7, vcc, 0, v5, vcc
	v_add_co_u32_e32 v4, vcc, s29, v4
	flat_load_ushort v81, v[6:7] offset:3584
	s_nop 0
	v_addc_co_u32_e32 v5, vcc, 0, v5, vcc
	flat_load_ushort v82, v[4:5] offset:3072
	v_ashrrev_i32_e32 v4, 31, v0
	v_add_u32_sdwa v4, v0, v4 dst_sel:DWORD dst_unused:UNUSED_PAD src0_sel:DWORD src1_sel:BYTE_3
	v_ashrrev_i32_e32 v57, 8, v4
	v_mul_i32_i24_e32 v4, 0x100, v57
	v_sub_u32_e32 v4, v0, v4
	v_lshlrev_b32_e32 v68, 1, v4
	v_and_b32_e32 v58, 0x7f, v4
	v_and_b32_e32 v0, 0xffffff00, v68
	v_lshlrev_b32_e32 v39, 5, v57
	v_or3_b32 v8, s45, v0, v58
	v_add_u32_e32 v0, s44, v39
	v_mov_b64_e32 v[6:7], s[26:27]
	v_mad_i64_i32 v[6:7], s[2:3], v0, s18, v[6:7]
	v_ashrrev_i32_e32 v9, 31, v8
	v_lshl_add_u64 v[12:13], v[8:9], 1, v[6:7]
	v_cmp_lt_i32_e64 s[38:39], s43, v39
	v_mov_b32_e32 v5, 0
	v_mov_b32_e32 v6, 0
	v_mov_b32_e32 v7, 0
	v_mov_b32_e32 v231, 0
	v_mov_b32_e32 v232, 0
	s_and_saveexec_b64 s[2:3], s[38:39]
	s_cbranch_execz .LBB0_77
	v_add_co_u32_e32 v6, vcc, 0x2000, v12
	s_nop 1
	v_addc_co_u32_e32 v7, vcc, 0, v13, vcc
	flat_load_ushort v231, v[6:7] offset:3584
	v_add_co_u32_e32 v6, vcc, 0x1000, v12
	s_nop 1
	v_addc_co_u32_e32 v7, vcc, 0, v13, vcc
	flat_load_ushort v232, v[6:7]
	s_nop 0
	s_nop 0
	s_nop 0
.LBB0_77:
	s_or_b64 exec, exec, s[2:3]
	v_mov_b32_e32 v233, 0
	s_and_saveexec_b64 s[2:3], s[38:39]
	s_cbranch_execz .LBB0_79
	v_add_co_u32_e32 v16, vcc, 0x4000, v12
	s_nop 1
	v_addc_co_u32_e32 v17, vcc, 0, v13, vcc
	flat_load_ushort v233, v[16:17] offset:3072
	s_nop 0
	s_nop 0

.LBB0_87:
	s_or_b64 exec, exec, s[2:3]
	v_readlane_b32 s2, v255, 25
	v_readlane_b32 s3, v255, 26
	s_add_u32 s54, s52, s2
	s_addc_u32 s55, s53, s3
	v_readlane_b32 s2, v255, 27
	v_lshlrev_b64 v[32:33], 2, v[10:11]
	s_add_u32 s52, s20, s2
	v_lshl_add_u64 v[12:13], s[54:55], 0, v[32:33]
	s_movk_i32 s2, 0x1000
	v_add_co_u32_e32 v10, vcc, s2, v12
	s_waitcnt lgkmcnt(0)
	s_barrier
	global_load_dword v17, v[12:13], off
	global_load_dword v16, v[12:13], off offset:3072
	v_addc_co_u32_e32 v11, vcc, 0, v13, vcc
	s_movk_i32 s2, 0x2000
	v_readlane_b32 s3, v255, 28
	v_add_co_u32_e32 v12, vcc, s2, v12
	s_addc_u32 s53, s21, s3
	global_load_dword v10, v[10:11], off offset:2048
	v_addc_co_u32_e32 v13, vcc, 0, v13, vcc
	global_load_dword v12, v[12:13], off offset:1024
	v_lshl_add_u64 v[32:33], s[52:53], 0, v[32:33]
	global_load_dword v14, v[32:33], off
	v_lshl_or_b32 v0, v92, 3, v178
	v_and_b32_e32 v102, 0x80, v18
	v_add_u32_e32 v0, v38, v0
	s_waitcnt vmcnt(5)
	v_lshlrev_b32_e32 v21, 16, v228
	v_lshlrev_b32_e32 v20, 16, v229
	v_lshlrev_b32_e32 v19, 16, v230
	v_lshlrev_b32_e32 v7, 16, v231
	v_lshlrev_b32_e32 v6, 16, v232
	v_lshlrev_b32_e32 v5, 16, v233
	v_mov_b32_e32 v18, v21
	ds_read_b32 v93, v0
	s_waitcnt vmcnt(0)
	v_lshlrev_b32_e32 v33, 16, v27
	v_lshlrev_b32_e32 v32, 16, v26
	v_lshlrev_b32_e32 v105, 16, v22
	v_mov_b32_e32 v104, v19
	s_movk_i32 s2, 0x80
	v_cmp_gt_u32_e64 s[38:39], s2, v15
	v_lshlrev_b32_e32 v25, 16, v24
	v_lshlrev_b32_e32 v24, 16, v23
	v_lshlrev_b32_e32 v23, 16, v30
	v_lshlrev_b32_e32 v30, 16, v28
	v_lshlrev_b32_e32 v31, 16, v29
	v_mov_b32_e32 v22, v25
	v_mov_b32_e32 v0, v17
	v_pk_mul_f32 v[26:27], v[18:19], v[16:17] op_sel_hi:[1,0]
	s_nop 0
	v_pk_fma_f32 v[20:21], v[20:21], v[0:1], v[26:27] op_sel_hi:[1,0,1]
	v_mov_b32_e32 v26, v105
	v_mov_b32_e32 v27, v32
	v_pk_fma_f32 v[20:21], v[104:105], v[10:11], v[20:21] op_sel_hi:[1,0,1]
	s_nop 0
	v_pk_fma_f32 v[20:21], v[12:13], v[26:27], v[20:21] op_sel_hi:[0,1,1]
	v_pk_add_f32 v[20:21], v[14:15], v[20:21] op_sel_hi:[0,1]
	v_mul_f32_e32 v11, 0xbfb8aa3b, v20
	v_exp_f32_e32 v26, v11
	v_mul_f32_e32 v11, 0xbfb8aa3b, v21
	v_exp_f32_e32 v27, v11
	s_nop 0
	v_pk_add_f32 v[26:27], v[26:27], 1.0 op_sel_hi:[1,0]
	s_nop 0
	v_div_scale_f32 v11, s[2:3], v27, v27, v21
	v_rcp_f32_e32 v13, v11
	s_nop 0
	v_fma_f32 v15, -v11, v13, 1.0
	v_fmac_f32_e32 v13, v15, v13
	v_div_scale_f32 v15, vcc, v21, v27, v21
	v_mul_f32_e32 v18, v15, v13
	v_fma_f32 v28, -v11, v18, v15
	v_fmac_f32_e32 v18, v28, v13
	v_fma_f32 v11, -v11, v18, v15
	v_div_fmas_f32 v11, v11, v13, v18
	v_div_fixup_f32 v27, v11, v27, v21
	v_div_scale_f32 v11, s[2:3], v26, v26, v20
	v_rcp_f32_e32 v13, v11
	v_mov_b32_e32 v28, v105
	v_fma_f32 v15, -v11, v13, 1.0
	v_fmac_f32_e32 v13, v15, v13
	v_div_scale_f32 v15, vcc, v20, v26, v20
	v_mul_f32_e32 v18, v15, v13
	v_fma_f32 v21, -v11, v18, v15
	v_fmac_f32_e32 v18, v21, v13
	v_fma_f32 v11, -v11, v18, v15
	v_div_fmas_f32 v11, v11, v13, v18
	v_mov_b32_e32 v18, v32
	v_pk_mul_f32 v[18:19], v[18:19], v[16:17]
	v_div_fixup_f32 v26, v11, v26, v20
	v_pk_fma_f32 v[18:19], v[16:17], v[28:29], v[18:19] op_sel:[0,0,1] op_sel_hi:[1,0,0]
	v_pk_mov_b32 v[20:21], v[32:33], v[30:31] op_sel:[1,0]
	v_pk_fma_f32 v[18:19], v[10:11], v[32:33], v[18:19] op_sel_hi:[0,1,1]
	v_pk_fma_f32 v[18:19], v[12:13], v[20:21], v[18:19] op_sel_hi:[0,1,1]
	v_pk_add_f32 v[18:19], v[14:15], v[18:19] op_sel_hi:[0,1]
	v_mul_f32_e32 v11, 0xbfb8aa3b, v18
	v_exp_f32_e32 v28, v11
	v_mul_f32_e32 v11, 0xbfb8aa3b, v19
	v_exp_f32_e32 v29, v11
	v_pk_mul_f32 v[20:21], v[16:17], v[20:21] op_sel_hi:[0,1]
	v_pk_fma_f32 v[20:21], v[0:1], v[32:33], v[20:21] op_sel_hi:[0,1,1]
	v_pk_add_f32 v[28:29], v[28:29], 1.0 op_sel_hi:[1,0]
	s_nop 0
	v_div_scale_f32 v11, s[2:3], v29, v29, v19
	v_rcp_f32_e32 v13, v11
	s_nop 0
	v_fma_f32 v15, -v11, v13, 1.0
	v_fmac_f32_e32 v13, v15, v13
	v_div_scale_f32 v15, vcc, v19, v29, v19
	v_mul_f32_e32 v103, v15, v13
	v_fma_f32 v104, -v11, v103, v15
	v_fmac_f32_e32 v103, v104, v13
	v_fma_f32 v11, -v11, v103, v15
	v_div_fmas_f32 v11, v11, v13, v103
	v_div_fixup_f32 v29, v11, v29, v19
	v_div_scale_f32 v11, s[2:3], v28, v28, v18
	v_rcp_f32_e32 v13, v11
	s_nop 0
	v_fma_f32 v15, -v11, v13, 1.0
	v_fmac_f32_e32 v13, v15, v13
	v_div_scale_f32 v15, vcc, v18, v28, v18
	v_mul_f32_e32 v19, v15, v13
	v_fma_f32 v103, -v11, v19, v15
	v_fmac_f32_e32 v19, v103, v13
	v_fma_f32 v11, -v11, v19, v15
	v_div_fmas_f32 v11, v11, v13, v19
	v_div_fixup_f32 v28, v11, v28, v18
	v_pk_mov_b32 v[18:19], v[30:31], v[24:25] op_sel:[1,0]
	v_pk_fma_f32 v[20:21], v[10:11], v[30:31], v[20:21] op_sel_hi:[0,1,1]
	v_pk_fma_f32 v[20:21], v[12:13], v[18:19], v[20:21] op_sel_hi:[0,1,1]
	v_pk_add_f32 v[20:21], v[14:15], v[20:21] op_sel_hi:[0,1]
	v_mul_f32_e32 v11, 0xbfb8aa3b, v20
	v_exp_f32_e32 v32, v11
	v_mul_f32_e32 v11, 0xbfb8aa3b, v21
	v_exp_f32_e32 v33, v11
	v_pk_mul_f32 v[18:19], v[16:17], v[18:19] op_sel_hi:[0,1]
	v_pk_fma_f32 v[18:19], v[0:1], v[30:31], v[18:19] op_sel_hi:[0,1,1]
	v_pk_add_f32 v[32:33], v[32:33], 1.0 op_sel_hi:[1,0]
	s_nop 0
	v_div_scale_f32 v11, s[2:3], v33, v33, v21
	v_rcp_f32_e32 v13, v11
	s_nop 0
	v_fma_f32 v15, -v11, v13, 1.0
	v_fmac_f32_e32 v13, v15, v13
	v_div_scale_f32 v15, vcc, v21, v33, v21
	v_mul_f32_e32 v103, v15, v13
	v_fma_f32 v104, -v11, v103, v15
	v_fmac_f32_e32 v103, v104, v13
	v_fma_f32 v11, -v11, v103, v15
	v_div_fmas_f32 v11, v11, v13, v103
	v_div_fixup_f32 v33, v11, v33, v21
	v_div_scale_f32 v11, s[2:3], v32, v32, v20
	v_rcp_f32_e32 v13, v11
	s_nop 0
	v_fma_f32 v15, -v11, v13, 1.0
	v_fmac_f32_e32 v13, v15, v13
	v_div_scale_f32 v15, vcc, v20, v32, v20
	v_mul_f32_e32 v21, v15, v13
	v_fma_f32 v103, -v11, v21, v15
	v_fmac_f32_e32 v21, v103, v13
	v_fma_f32 v11, -v11, v21, v15
	v_div_fmas_f32 v11, v11, v13, v21
	v_pk_fma_f32 v[18:19], v[10:11], v[24:25], v[18:19] op_sel_hi:[0,1,1]
	v_pk_fma_f32 v[18:19], v[12:13], v[22:23], v[18:19] op_sel_hi:[0,1,1]
	v_pk_add_f32 v[18:19], v[14:15], v[18:19] op_sel_hi:[0,1]
	v_mul_f32_e32 v0, 0xbfb8aa3b, v18
	v_div_fixup_f32 v32, v11, v32, v20
	v_exp_f32_e32 v20, v0
	v_mul_f32_e32 v0, 0xbfb8aa3b, v19
	v_exp_f32_e32 v21, v0
	v_mov_b32_e32 v103, v36
	v_pk_add_f32 v[20:21], v[20:21], 1.0 op_sel_hi:[1,0]
	s_nop 0
	v_div_scale_f32 v0, s[2:3], v21, v21, v19
	v_rcp_f32_e32 v11, v0
	s_nop 0
	v_fma_f32 v13, -v0, v11, 1.0
	v_fmac_f32_e32 v11, v13, v11
	v_div_scale_f32 v13, vcc, v19, v21, v19
	v_mul_f32_e32 v15, v13, v11
	v_fma_f32 v30, -v0, v15, v13
	v_fmac_f32_e32 v15, v30, v11
	v_fma_f32 v0, -v0, v15, v13
	v_div_fmas_f32 v0, v0, v11, v15
	v_div_fixup_f32 v31, v0, v21, v19
	v_div_scale_f32 v0, s[2:3], v20, v20, v18
	v_rcp_f32_e32 v11, v0
	s_nop 0
	v_fma_f32 v13, -v0, v11, 1.0
	v_fmac_f32_e32 v11, v13, v11
	v_div_scale_f32 v13, vcc, v18, v20, v18
	v_mul_f32_e32 v15, v13, v11
	v_fma_f32 v19, -v0, v15, v13
	v_fmac_f32_e32 v15, v19, v11
	v_fma_f32 v0, -v0, v15, v13
	v_div_fmas_f32 v0, v0, v11, v15
	v_div_fixup_f32 v30, v0, v20, v18
	s_and_saveexec_b64 s[20:21], s[38:39]
	s_cbranch_execz .LBB0_89
	v_add_u32_e32 v0, v102, v67
	v_lshl_add_u32 v0, v0, 2, v38
	v_add_u32_e32 v13, 0x800, v0
	ds_read2_b32 v[18:19], v13 offset1:1
	v_add_u32_e32 v11, 0x400, v0
	ds_read2_b32 v[20:21], v11 offset1:1
	v_add_u32_e32 v11, 0x408, v0
	v_mov_b32_e32 v103, v37
	s_waitcnt lgkmcnt(1)
	v_sub_f32_e32 v13, v93, v18
	v_mul_f32_e32 v13, 0x3fb8aa3b, v13
	v_exp_f32_e32 v18, v13
	v_sub_f32_e32 v13, v93, v19
	v_mul_f32_e32 v13, 0x3fb8aa3b, v13
	v_exp_f32_e32 v19, v13
	v_add_u32_e32 v13, 0x808, v0
	s_waitcnt lgkmcnt(0)
	v_pk_mul_f32 v[18:19], v[20:21], v[18:19]
	s_nop 0
	v_pk_mul_f32 v[26:27], v[26:27], v[18:19]
	ds_read2_b32 v[18:19], v13 offset1:1
	ds_read2_b32 v[20:21], v11 offset1:1
	v_add_u32_e32 v11, 0x410, v0
	s_waitcnt lgkmcnt(1)
	v_sub_f32_e32 v13, v93, v18
	v_mul_f32_e32 v13, 0x3fb8aa3b, v13
	v_exp_f32_e32 v18, v13
	v_sub_f32_e32 v13, v93, v19
	v_mul_f32_e32 v13, 0x3fb8aa3b, v13
	v_exp_f32_e32 v19, v13
	v_add_u32_e32 v13, 0x810, v0
	s_waitcnt lgkmcnt(0)
	v_pk_mul_f32 v[18:19], v[20:21], v[18:19]
	s_nop 0
	v_pk_mul_f32 v[28:29], v[28:29], v[18:19]
	ds_read2_b32 v[18:19], v13 offset1:1
	ds_read2_b32 v[20:21], v11 offset1:1
	v_add_u32_e32 v11, 0x418, v0
	v_add_u32_e32 v0, 0x818, v0
	s_waitcnt lgkmcnt(1)
	v_sub_f32_e32 v13, v93, v18
	v_mul_f32_e32 v13, 0x3fb8aa3b, v13
	v_exp_f32_e32 v18, v13
	v_sub_f32_e32 v13, v93, v19
	v_mul_f32_e32 v13, 0x3fb8aa3b, v13
	v_exp_f32_e32 v19, v13
	s_waitcnt lgkmcnt(0)
	v_pk_mul_f32 v[18:19], v[20:21], v[18:19]
	s_nop 0
	v_pk_mul_f32 v[32:33], v[32:33], v[18:19]
	ds_read2_b32 v[18:19], v0 offset1:1
	ds_read2_b32 v[20:21], v11 offset1:1
	s_waitcnt lgkmcnt(1)
	v_sub_f32_e32 v0, v93, v18
	v_mul_f32_e32 v0, 0x3fb8aa3b, v0
	v_exp_f32_e32 v18, v0
	v_sub_f32_e32 v0, v93, v19
	v_mul_f32_e32 v0, 0x3fb8aa3b, v0
	v_exp_f32_e32 v19, v0
	s_waitcnt lgkmcnt(0)
	v_pk_mul_f32 v[18:19], v[20:21], v[18:19]
	s_nop 0
	v_pk_mul_f32 v[30:31], v[30:31], v[18:19]

.LBB0_173:
	s_and_b64 vcc, exec, s[2:3]
	s_cbranch_vccz .LBB0_253
	s_add_i32 s2, s85, 0xfffffe00
	s_lshr_b32 s2, s2, 7
	s_bfe_u32 s3, s85, 0x60001
	s_and_b32 s6, s85, 1
	s_lshl_b32 s7, s3, 7
	s_lshl_b32 s10, s2, 8
	s_lshl_b32 s3, s3, 2
	s_lshl_b32 s2, s2, 13
	s_lshl_b32 s54, s6, 1
	s_or_b32 s3, s3, s10
	s_or_b32 s52, s7, s2
	s_mov_b32 s2, 14
	s_or_b32 s38, s3, s54
	s_ashr_i32 s3, s2, 31
	s_lshl_b32 s53, s6, 7
	s_add_i32 s58, s52, -3
	s_sub_i32 s57, 0, s7
	s_lshl_b64 s[2:3], s[2:3], 3
	s_add_u32 s2, s0, s2
	s_mov_b32 s6, 15
	s_addc_u32 s3, s1, s3
	s_ashr_i32 s7, s6, 31
	s_lshl_b64 s[6:7], s[6:7], 3
	s_add_u32 s6, s0, s6
	s_mov_b32 s10, 16
	s_addc_u32 s7, s1, s7
	s_ashr_i32 s11, s10, 31
	s_lshl_b64 s[10:11], s[10:11], 3
	s_add_u32 s10, s0, s10
	s_mov_b32 s20, 17
	s_addc_u32 s11, s1, s11
	s_ashr_i32 s21, s20, 31
	s_lshl_b64 s[20:21], s[20:21], 3
	s_add_u32 s40, s0, s20
	s_mov_b32 s20, 18
	s_addc_u32 s41, s1, s21
	s_ashr_i32 s21, s20, 31
	s_lshl_b64 s[20:21], s[20:21], 3
	s_add_u32 s42, s0, s20
	s_mov_b32 s20, 19
	s_addc_u32 s43, s1, s21
	s_ashr_i32 s21, s20, 31
	s_lshl_b64 s[20:21], s[20:21], 3
	s_add_u32 s50, s0, s20
	v_mov_b32_e32 v104, v183
	v_readlane_b32 s20, v254, 53
	s_addc_u32 s51, s1, s21
	v_readfirstlane_b32 s55, v104
	v_mov_b32_e32 v99, s20
	v_readlane_b32 s20, v254, 54
	s_ashr_i32 s56, s55, 8
	v_lshrrev_b32_e32 v0, 1, v104
	v_mov_b32_e32 v103, s20
	v_readlane_b32 s20, v254, 55
	v_and_b32_e32 v0, 16, v0
	v_and_b32_e32 v98, 63, v104
	v_mov_b32_e32 v101, s20
	s_add_i32 s20, s38, s56
	s_ashr_i32 s21, s20, 31
	s_lshl_b64 s[20:21], s[20:21], 14
	v_readlane_b32 s38, v254, 62
	v_readlane_b32 s39, v254, 63
	s_add_u32 s20, s38, s20
	s_addc_u32 s21, s39, s21
	v_lshl_add_u64 v[6:7], s[20:21], 0, v[0:1]
	v_lshlrev_b32_e32 v0, 8, v104
	v_and_b32_e32 v0, 0x1f00, v0
	v_lshl_add_u64 v[8:9], v[6:7], 0, v[0:1]
	v_mov_b32_e32 v0, 0x2000
	v_lshl_or_b32 v0, v98, 8, v0
	v_mov_b32_e32 v102, v1
	v_lshl_add_u64 v[6:7], v[6:7], 0, v[0:1]
	s_waitcnt lgkmcnt(0)
	s_barrier
	global_load_dwordx4 v[2:5], v[8:9], off
	global_load_dwordx4 v[78:81], v[8:9], off offset:32
	global_load_dwordx4 v[74:77], v[8:9], off offset:64
	global_load_dwordx4 v[66:69], v[8:9], off offset:96
	global_load_dwordx4 v[58:61], v[8:9], off offset:128
	global_load_dwordx4 v[54:57], v[8:9], off offset:160
	global_load_dwordx4 v[46:49], v[8:9], off offset:192
	global_load_dwordx4 v[38:41], v[8:9], off offset:224
	global_load_dwordx4 v[18:21], v[6:7], off
	global_load_dwordx4 v[86:89], v[6:7], off offset:32
	global_load_dwordx4 v[82:85], v[6:7], off offset:64
	global_load_dwordx4 v[70:73], v[6:7], off offset:96
	global_load_dwordx4 v[62:65], v[6:7], off offset:128
	global_load_dwordx4 v[50:53], v[6:7], off offset:160
	global_load_dwordx4 v[42:45], v[6:7], off offset:192
	global_load_dwordx4 v[34:37], v[6:7], off offset:224
	s_mov_b32 s20, 0x2aaaaaab
	v_mul_hi_i32 v0, v104, s20
	v_lshrrev_b32_e32 v6, 31, v0
	v_ashrrev_i32_e32 v0, 6, v0
	v_add_u32_e32 v25, v0, v6
	v_mul_i32_i24_e32 v0, 0x180, v25
	v_sub_u32_e32 v14, v104, v0
	v_lshlrev_b32_e32 v213, 1, v14
	v_and_b32_e32 v27, 0x7f, v14
	v_and_b32_e32 v0, 0xffffff00, v213
	v_lshlrev_b32_e32 v10, 5, v25
	v_or3_b32 v6, s53, v0, v27
	v_add_u32_e32 v0, s58, v10
	v_mov_b64_e32 v[8:9], s[26:27]
	v_mad_i64_i32 v[8:9], s[20:21], v0, s18, v[8:9]
	v_ashrrev_i32_e32 v7, 31, v6
	v_lshl_add_u64 v[6:7], v[6:7], 1, v[8:9]
	v_cmp_lt_i32_e64 s[38:39], s57, v10
	v_mov_b32_e32 v15, 0
	v_mov_b32_e32 v16, 0
	v_mov_b32_e32 v17, 0
	v_mov_b32_e32 v228, 0
	v_mov_b32_e32 v229, 0
	s_and_saveexec_b64 s[20:21], s[38:39]
	s_cbranch_execz .LBB0_176
	v_add_co_u32_e32 v8, vcc, 0x2000, v6
	s_nop 1
	v_addc_co_u32_e32 v9, vcc, 0, v7, vcc
	flat_load_ushort v228, v[8:9] offset:3584
	v_add_co_u32_e32 v8, vcc, 0x1000, v6
	s_nop 0
	s_nop 0
	v_addc_co_u32_e32 v9, vcc, 0, v7, vcc
	flat_load_ushort v229, v[8:9]
	s_nop 0
	s_nop 0
.LBB0_176:
	s_or_b64 exec, exec, s[20:21]
	s_load_dwordx2 s[46:47], s[2:3], 0x0
	s_load_dwordx2 s[44:45], s[6:7], 0x0
	s_load_dwordx2 s[20:21], s[10:11], 0x0
	s_load_dwordx2 s[48:49], s[40:41], 0x0
	s_nop 0
	s_load_dwordx2 s[42:43], s[42:43], 0x0
	s_nop 0
	s_load_dwordx2 s[40:41], s[50:51], 0x0
	v_mov_b32_e32 v230, 0
	s_and_saveexec_b64 s[2:3], s[38:39]
	s_cbranch_execz .LBB0_178
	v_add_co_u32_e32 v8, vcc, 0x4000, v6
	s_nop 1
	v_addc_co_u32_e32 v9, vcc, 0, v7, vcc
	flat_load_ushort v230, v[8:9] offset:3072
	s_nop 0
	s_nop 0
.LBB0_178:
	s_or_b64 exec, exec, s[2:3]
	v_add_co_u32_e32 v8, vcc, 0x6000, v6
	s_mov_b32 s2, 0xc000
	s_nop 0
	v_addc_co_u32_e32 v9, vcc, 0, v7, vcc
	flat_load_ushort v92, v[8:9] offset:2560
	v_add_co_u32_e32 v8, vcc, 0x8000, v6
	v_add_u32_e32 v0, 0x200, v104
	s_nop 0
	v_addc_co_u32_e32 v9, vcc, 0, v7, vcc
	flat_load_ushort v93, v[8:9] offset:2048
	v_add_co_u32_e32 v8, vcc, 0xa000, v6
	v_mov_b32_e32 v11, 0
	s_nop 0
	v_addc_co_u32_e32 v9, vcc, 0, v7, vcc
	flat_load_ushort v30, v[8:9] offset:1536
	v_add_co_u32_e32 v8, vcc, s2, v6
	s_mov_b32 s2, 0x11000
	s_nop 0
	v_addc_co_u32_e32 v9, vcc, 0, v7, vcc
	flat_load_ushort v31, v[8:9] offset:1024
	v_add_co_u32_e32 v8, vcc, 0xe000, v6
	v_mov_b32_e32 v12, 0
	s_nop 0
	v_addc_co_u32_e32 v9, vcc, 0, v7, vcc
	flat_load_ushort v32, v[8:9] offset:512
	v_add_co_u32_e32 v8, vcc, s28, v6
	v_mov_b32_e32 v13, 0
	s_nop 0
	v_addc_co_u32_e32 v9, vcc, 0, v7, vcc
	flat_load_ushort v90, v[8:9]
	v_add_co_u32_e32 v8, vcc, s2, v6
	s_mov_b32 s2, 0x20000
	s_nop 0
	v_addc_co_u32_e32 v9, vcc, 0, v7, vcc
	flat_load_ushort v33, v[8:9] offset:3584
	v_add_co_u32_e32 v8, vcc, 0x13000, v6
	s_nop 1
	v_addc_co_u32_e32 v9, vcc, 0, v7, vcc
	flat_load_ushort v91, v[8:9] offset:3072
	v_add_co_u32_e32 v8, vcc, 0x15000, v6
	s_nop 1
	v_addc_co_u32_e32 v9, vcc, 0, v7, vcc
	flat_load_ushort v214, v[8:9] offset:2560
	v_add_co_u32_e32 v8, vcc, 0x17000, v6
	s_nop 1
	v_addc_co_u32_e32 v9, vcc, 0, v7, vcc
	flat_load_ushort v215, v[8:9] offset:2048
	v_add_co_u32_e32 v8, vcc, 0x19000, v6
	s_nop 1
	v_addc_co_u32_e32 v9, vcc, 0, v7, vcc
	flat_load_ushort v211, v[8:9] offset:1536
	v_add_co_u32_e32 v8, vcc, 0x1b000, v6
	s_nop 1
	v_addc_co_u32_e32 v9, vcc, 0, v7, vcc
	flat_load_ushort v212, v[8:9] offset:1024
	v_add_co_u32_e32 v8, vcc, 0x1d000, v6
	s_nop 1
	v_addc_co_u32_e32 v9, vcc, 0, v7, vcc
	flat_load_ushort v94, v[8:9] offset:512
	v_add_co_u32_e32 v8, vcc, 0x1f000, v6
	s_nop 1
	v_addc_co_u32_e32 v9, vcc, 0, v7, vcc
	flat_load_ushort v95, v[8:9]
	v_add_co_u32_e32 v8, vcc, s2, v6
	s_mov_b32 s2, 0x28000
	s_nop 0
	v_addc_co_u32_e32 v9, vcc, 0, v7, vcc
	flat_load_ushort v96, v[8:9] offset:3584
	v_add_co_u32_e32 v8, vcc, 0x22000, v6
	s_nop 1
	v_addc_co_u32_e32 v9, vcc, 0, v7, vcc
	flat_load_ushort v97, v[8:9] offset:3072
	v_add_co_u32_e32 v8, vcc, 0x24000, v6
	s_nop 1
	v_addc_co_u32_e32 v9, vcc, 0, v7, vcc
	flat_load_ushort v209, v[8:9] offset:2560
	v_add_co_u32_e32 v8, vcc, 0x26000, v6
	s_nop 1
	v_addc_co_u32_e32 v9, vcc, 0, v7, vcc
	flat_load_ushort v210, v[8:9] offset:2048
	v_add_co_u32_e32 v8, vcc, s2, v6
	s_mov_b32 s2, 0x2aaaaaab
	s_nop 0
	v_addc_co_u32_e32 v9, vcc, 0, v7, vcc
	flat_load_ushort v207, v[8:9] offset:1536
	v_add_co_u32_e32 v8, vcc, 0x2a000, v6
	s_nop 1
	v_addc_co_u32_e32 v9, vcc, 0, v7, vcc
	flat_load_ushort v208, v[8:9] offset:1024
	v_add_co_u32_e32 v8, vcc, 0x2c000, v6
	s_nop 1
	v_addc_co_u32_e32 v9, vcc, 0, v7, vcc
	flat_load_ushort v203, v[8:9] offset:512
	v_add_co_u32_e32 v8, vcc, 0x2e000, v6
	s_nop 1
	v_addc_co_u32_e32 v9, vcc, 0, v7, vcc
	flat_load_ushort v204, v[8:9]
	v_add_co_u32_e32 v8, vcc, 0x2f000, v6
	s_nop 1
	v_addc_co_u32_e32 v9, vcc, 0, v7, vcc
	flat_load_ushort v205, v[8:9] offset:3584
	v_add_co_u32_e32 v8, vcc, 0x31000, v6
	s_nop 1
	v_addc_co_u32_e32 v9, vcc, 0, v7, vcc
	flat_load_ushort v206, v[8:9] offset:3072
	v_add_co_u32_e32 v8, vcc, 0x33000, v6
	s_nop 1
	v_addc_co_u32_e32 v9, vcc, 0, v7, vcc
	flat_load_ushort v201, v[8:9] offset:2560
	v_add_co_u32_e32 v8, vcc, 0x35000, v6
	s_nop 1
	v_addc_co_u32_e32 v9, vcc, 0, v7, vcc
	flat_load_ushort v202, v[8:9] offset:2048
	v_add_co_u32_e32 v8, vcc, 0x37000, v6
	s_nop 1
	v_addc_co_u32_e32 v9, vcc, 0, v7, vcc
	flat_load_ushort v199, v[8:9] offset:1536
	v_add_co_u32_e32 v8, vcc, 0x39000, v6
	s_nop 1
	v_addc_co_u32_e32 v9, vcc, 0, v7, vcc
	flat_load_ushort v200, v[8:9] offset:1024
	v_add_co_u32_e32 v8, vcc, 0x3b000, v6
	s_nop 1
	v_addc_co_u32_e32 v9, vcc, 0, v7, vcc
	flat_load_ushort v197, v[8:9] offset:512
	v_add_co_u32_e32 v8, vcc, 0x3d000, v6
	s_nop 1
	v_addc_co_u32_e32 v9, vcc, 0, v7, vcc
	flat_load_ushort v198, v[8:9]
	v_add_co_u32_e32 v8, vcc, 0x3e000, v6
	s_nop 1
	v_addc_co_u32_e32 v9, vcc, 0, v7, vcc
	v_add_co_u32_e32 v6, vcc, s29, v6
	flat_load_ushort v195, v[8:9] offset:3584
	s_nop 0
	v_addc_co_u32_e32 v7, vcc, 0, v7, vcc
	flat_load_ushort v196, v[6:7] offset:3072
	v_mul_hi_i32 v6, v0, s2
	v_lshrrev_b32_e32 v7, 31, v6
	v_ashrrev_i32_e32 v6, 6, v6
	v_add_u32_e32 v161, v6, v7
	v_mul_i32_i24_e32 v6, 0x180, v161
	v_sub_u32_e32 v192, v0, v6
	v_lshlrev_b32_e32 v185, 1, v192
	v_and_b32_e32 v169, 0x7f, v192
	v_and_b32_e32 v0, 0xffffff00, v185
	v_lshlrev_b32_e32 v135, 5, v161
	v_or3_b32 v6, s53, v0, v169
	v_add_u32_e32 v0, s58, v135
	v_mov_b64_e32 v[8:9], s[26:27]
	v_mad_i64_i32 v[8:9], s[2:3], v0, s18, v[8:9]
	v_ashrrev_i32_e32 v7, 31, v6
	v_lshl_add_u64 v[6:7], v[6:7], 1, v[8:9]
	v_cmp_lt_i32_e64 s[38:39], s57, v135
	v_mov_b32_e32 v231, 0
	v_mov_b32_e32 v232, 0
	s_and_saveexec_b64 s[2:3], s[38:39]
	s_cbranch_execz .LBB0_180
	v_add_co_u32_e32 v8, vcc, 0x2000, v6
	s_nop 1
	v_addc_co_u32_e32 v9, vcc, 0, v7, vcc
	flat_load_ushort v231, v[8:9] offset:3584
	v_add_co_u32_e32 v8, vcc, 0x1000, v6
	s_nop 0
	s_nop 0
	v_addc_co_u32_e32 v9, vcc, 0, v7, vcc
	flat_load_ushort v232, v[8:9]
	s_nop 0
	s_nop 0
.LBB0_180:
	s_or_b64 exec, exec, s[2:3]
	v_mov_b32_e32 v233, 0
	s_and_saveexec_b64 s[2:3], s[38:39]
	s_cbranch_execz .LBB0_182
	v_add_co_u32_e32 v8, vcc, 0x4000, v6
	s_nop 1
	v_addc_co_u32_e32 v9, vcc, 0, v7, vcc
	flat_load_ushort v233, v[8:9] offset:3072
	s_nop 0
	s_nop 0
.LBB0_182:
	s_or_b64 exec, exec, s[2:3]
	v_add_co_u32_e32 v8, vcc, 0x6000, v6
	s_mov_b32 s2, 0xc000
	s_nop 0
	v_addc_co_u32_e32 v9, vcc, 0, v7, vcc
	flat_load_ushort v193, v[8:9] offset:2560
	v_add_co_u32_e32 v8, vcc, 0x8000, v6
	v_add_u32_e32 v0, 0x400, v104
	s_nop 0
	v_addc_co_u32_e32 v9, vcc, 0, v7, vcc
	flat_load_ushort v194, v[8:9] offset:2048
	v_add_co_u32_e32 v8, vcc, 0xa000, v6
	s_nop 1
	v_addc_co_u32_e32 v9, vcc, 0, v7, vcc
	flat_load_ushort v190, v[8:9] offset:1536
	v_add_co_u32_e32 v8, vcc, s2, v6
	s_mov_b32 s2, 0x11000
	s_nop 0
	v_addc_co_u32_e32 v9, vcc, 0, v7, vcc
	flat_load_ushort v191, v[8:9] offset:1024
	v_add_co_u32_e32 v8, vcc, 0xe000, v6
	s_nop 1
	v_addc_co_u32_e32 v9, vcc, 0, v7, vcc
	flat_load_ushort v186, v[8:9] offset:512
	v_add_co_u32_e32 v8, vcc, s28, v6
	s_nop 1
	v_addc_co_u32_e32 v9, vcc, 0, v7, vcc
	flat_load_ushort v187, v[8:9]
	v_add_co_u32_e32 v8, vcc, s2, v6
	s_mov_b32 s2, 0x20000
	s_nop 0
	v_addc_co_u32_e32 v9, vcc, 0, v7, vcc
	flat_load_ushort v188, v[8:9] offset:3584
	v_add_co_u32_e32 v8, vcc, 0x13000, v6
	s_nop 1
	v_addc_co_u32_e32 v9, vcc, 0, v7, vcc
	flat_load_ushort v189, v[8:9] offset:3072
	v_add_co_u32_e32 v8, vcc, 0x15000, v6
	s_nop 1
	v_addc_co_u32_e32 v9, vcc, 0, v7, vcc
	flat_load_ushort v168, v[8:9] offset:2560
	v_add_co_u32_e32 v8, vcc, 0x17000, v6
	s_nop 1
	v_addc_co_u32_e32 v9, vcc, 0, v7, vcc
	flat_load_ushort v184, v[8:9] offset:2048
	v_add_co_u32_e32 v8, vcc, 0x19000, v6
	s_nop 1
	v_addc_co_u32_e32 v9, vcc, 0, v7, vcc
	flat_load_ushort v166, v[8:9] offset:1536
	v_add_co_u32_e32 v8, vcc, 0x1b000, v6
	s_nop 1
	v_addc_co_u32_e32 v9, vcc, 0, v7, vcc
	flat_load_ushort v167, v[8:9] offset:1024
	v_add_co_u32_e32 v8, vcc, 0x1d000, v6
	s_nop 1
	v_addc_co_u32_e32 v9, vcc, 0, v7, vcc
	flat_load_ushort v162, v[8:9] offset:512
	v_add_co_u32_e32 v8, vcc, 0x1f000, v6
	s_nop 1
	v_addc_co_u32_e32 v9, vcc, 0, v7, vcc
	flat_load_ushort v163, v[8:9]
	v_add_co_u32_e32 v8, vcc, s2, v6
	s_mov_b32 s2, 0x28000
	s_nop 0
	v_addc_co_u32_e32 v9, vcc, 0, v7, vcc
	flat_load_ushort v164, v[8:9] offset:3584
	v_add_co_u32_e32 v8, vcc, 0x22000, v6
	s_nop 1
	v_addc_co_u32_e32 v9, vcc, 0, v7, vcc
	flat_load_ushort v165, v[8:9] offset:3072
	v_add_co_u32_e32 v8, vcc, 0x24000, v6
	s_nop 1
	v_addc_co_u32_e32 v9, vcc, 0, v7, vcc
	s_waitcnt vmcnt(0)
	flat_load_ushort v159, v[8:9] offset:2560
	v_add_co_u32_e32 v8, vcc, 0x26000, v6
	s_nop 1
	v_addc_co_u32_e32 v9, vcc, 0, v7, vcc
	flat_load_ushort v160, v[8:9] offset:2048
	v_add_co_u32_e32 v8, vcc, s2, v6
	s_mov_b32 s2, 0x2aaaaaab
	s_nop 0
	v_addc_co_u32_e32 v9, vcc, 0, v7, vcc
	flat_load_ushort v157, v[8:9] offset:1536
	v_add_co_u32_e32 v8, vcc, 0x2a000, v6
	s_nop 1
	v_addc_co_u32_e32 v9, vcc, 0, v7, vcc
	flat_load_ushort v158, v[8:9] offset:1024
	v_add_co_u32_e32 v8, vcc, 0x2c000, v6
	s_nop 1
	v_addc_co_u32_e32 v9, vcc, 0, v7, vcc
	flat_load_ushort v153, v[8:9] offset:512
	v_add_co_u32_e32 v8, vcc, 0x2e000, v6
	s_nop 1
	v_addc_co_u32_e32 v9, vcc, 0, v7, vcc
	flat_load_ushort v154, v[8:9]
	v_add_co_u32_e32 v8, vcc, 0x2f000, v6
	s_nop 1
	v_addc_co_u32_e32 v9, vcc, 0, v7, vcc
	flat_load_ushort v155, v[8:9] offset:3584
	v_add_co_u32_e32 v8, vcc, 0x31000, v6
	s_nop 1
	v_addc_co_u32_e32 v9, vcc, 0, v7, vcc
	flat_load_ushort v156, v[8:9] offset:3072
	v_add_co_u32_e32 v8, vcc, 0x33000, v6
	s_nop 1
	v_addc_co_u32_e32 v9, vcc, 0, v7, vcc
	flat_load_ushort v151, v[8:9] offset:2560
	v_add_co_u32_e32 v8, vcc, 0x35000, v6
	s_nop 1
	v_addc_co_u32_e32 v9, vcc, 0, v7, vcc
	flat_load_ushort v152, v[8:9] offset:2048
	v_add_co_u32_e32 v8, vcc, 0x37000, v6
	s_nop 1
	v_addc_co_u32_e32 v9, vcc, 0, v7, vcc
	flat_load_ushort v149, v[8:9] offset:1536
	v_add_co_u32_e32 v8, vcc, 0x39000, v6
	s_nop 1
	v_addc_co_u32_e32 v9, vcc, 0, v7, vcc
	flat_load_ushort v150, v[8:9] offset:1024
	v_add_co_u32_e32 v8, vcc, 0x3b000, v6
	s_nop 1
	v_addc_co_u32_e32 v9, vcc, 0, v7, vcc
	flat_load_ushort v147, v[8:9] offset:512
	v_add_co_u32_e32 v8, vcc, 0x3d000, v6
	s_nop 1
	v_addc_co_u32_e32 v9, vcc, 0, v7, vcc
	flat_load_ushort v148, v[8:9]
	v_add_co_u32_e32 v8, vcc, 0x3e000, v6
	s_nop 1
	v_addc_co_u32_e32 v9, vcc, 0, v7, vcc
	v_add_co_u32_e32 v6, vcc, s29, v6
	flat_load_ushort v143, v[8:9] offset:3584
	s_nop 0
	v_addc_co_u32_e32 v7, vcc, 0, v7, vcc
	flat_load_ushort v144, v[6:7] offset:3072
	v_mul_hi_i32 v6, v0, s2
	v_lshrrev_b32_e32 v7, 31, v6
	v_ashrrev_i32_e32 v6, 6, v6
	v_add_u32_e32 v122, v6, v7
	v_mul_i32_i24_e32 v6, 0x180, v122
	v_sub_u32_e32 v140, v0, v6
	v_lshlrev_b32_e32 v132, 1, v140
	v_and_b32_e32 v130, 0x7f, v140
	v_and_b32_e32 v0, 0xffffff00, v132
	v_lshlrev_b32_e32 v100, 5, v122
	v_or3_b32 v6, s53, v0, v130
	v_add_u32_e32 v0, s58, v100
	v_mov_b64_e32 v[8:9], s[26:27]
	v_mad_i64_i32 v[8:9], s[2:3], v0, s18, v[8:9]
	v_ashrrev_i32_e32 v7, 31, v6
	v_lshl_add_u64 v[22:23], v[6:7], 1, v[8:9]
	v_cmp_lt_i32_e64 s[38:39], s57, v100
	v_mov_b32_e32 v7, 0
	v_mov_b32_e32 v8, 0
	v_mov_b32_e32 v9, 0
	v_mov_b32_e32 v234, 0
	v_mov_b32_e32 v235, 0
	s_and_saveexec_b64 s[2:3], s[38:39]
	s_cbranch_execz .LBB0_184
	v_add_co_u32_e32 v8, vcc, 0x2000, v22
	s_nop 1
	v_addc_co_u32_e32 v9, vcc, 0, v23, vcc
	flat_load_ushort v234, v[8:9] offset:3584
	v_add_co_u32_e32 v8, vcc, 0x1000, v22
	s_nop 1
	v_addc_co_u32_e32 v9, vcc, 0, v23, vcc
	flat_load_ushort v235, v[8:9]
	s_nop 0
	s_nop 0
	s_nop 0
.LBB0_184:
	s_or_b64 exec, exec, s[2:3]
	v_mov_b32_e32 v236, 0
	s_and_saveexec_b64 s[2:3], s[38:39]
	s_cbranch_execz .LBB0_186
	v_add_co_u32_e32 v6, vcc, 0x4000, v22
	s_nop 1
	v_addc_co_u32_e32 v7, vcc, 0, v23, vcc
	flat_load_ushort v236, v[6:7] offset:3072
	s_nop 0
	s_nop 0

.LBB0_194:
	s_or_b64 exec, exec, s[2:3]
	v_ashrrev_i32_e32 v0, 7, v14
	v_lshlrev_b32_e32 v6, 8, v0
	v_or3_b32 v22, v6, s53, v27
	s_add_u32 s46, s46, s4
	v_ashrrev_i32_e32 v23, 31, v22
	s_addc_u32 s47, s47, s5
	v_readlane_b32 s2, v254, 58
	v_lshlrev_b64 v[216:217], 2, v[22:23]
	v_lshl_add_u64 v[218:219], s[46:47], 0, v[216:217]
	v_mov_b32_e32 v105, s2
	s_movk_i32 s2, 0x1000
	v_add_co_u32_e32 v22, vcc, s2, v218
	s_waitcnt lgkmcnt(0)
	s_barrier
	global_load_dword v29, v[218:219], off
	global_load_dword v28, v[218:219], off offset:3072
	v_addc_co_u32_e32 v23, vcc, 0, v219, vcc
	s_movk_i32 s2, 0x2000
	s_add_u32 s44, s44, s90
	v_add_co_u32_e32 v218, vcc, s2, v218
	s_addc_u32 s45, s45, s91
	global_load_dword v22, v[22:23], off offset:2048
	v_addc_co_u32_e32 v219, vcc, 0, v219, vcc
	global_load_dword v24, v[218:219], off offset:1024
	v_lshl_add_u64 v[216:217], s[44:45], 0, v[216:217]
	global_load_dword v26, v[216:217], off
	s_movk_i32 s2, 0x7f
	v_cmp_lt_u32_e64 s[38:39], s2, v14
	s_waitcnt vmcnt(5)
	v_lshlrev_b32_e32 v17, 16, v228
	v_lshlrev_b32_e32 v16, 16, v229
	v_lshlrev_b32_e32 v15, 16, v230
	v_lshlrev_b32_e32 v13, 16, v231
	v_lshlrev_b32_e32 v12, 16, v232
	v_lshlrev_b32_e32 v11, 16, v233
	v_lshlrev_b32_e32 v9, 16, v234
	v_lshlrev_b32_e32 v8, 16, v235
	v_lshlrev_b32_e32 v7, 16, v236
	v_mov_b32_e32 v14, v17
	v_lshlrev_b32_e32 v93, 16, v93
	v_lshlrev_b32_e32 v92, 16, v92
	v_cmp_eq_u32_e32 vcc, 1, v0
	v_lshlrev_b32_e32 v31, 16, v31
	v_lshlrev_b32_e32 v30, 16, v30
	v_cndmask_b32_e32 v0, v99, v102, vcc
	v_lshlrev_b32_e32 v33, 16, v33
	v_lshlrev_b32_e32 v91, 16, v91
	v_lshl_add_u32 v0, v27, 1, v0
	s_waitcnt vmcnt(0)
	v_mov_b32_e32 v6, v29
	v_pk_mul_f32 v[216:217], v[14:15], v[28:29] op_sel_hi:[1,0]
	s_nop 0
	v_pk_fma_f32 v[16:17], v[16:17], v[6:7], v[216:217] op_sel_hi:[1,0,1]
	v_pk_mov_b32 v[216:217], v[14:15], v[92:93] op_sel:[1,0]
	s_nop 0
	v_pk_fma_f32 v[16:17], v[216:217], v[22:23], v[16:17] op_sel_hi:[1,0,1]
	s_nop 0
	v_pk_fma_f32 v[16:17], v[24:25], v[92:93], v[16:17] op_sel_hi:[0,1,1]
	v_pk_add_f32 v[16:17], v[26:27], v[16:17] op_sel_hi:[0,1]
	v_mul_f32_e32 v14, 0xbfb8aa3b, v16
	v_exp_f32_e32 v216, v14
	v_mul_f32_e32 v14, 0xbfb8aa3b, v17
	v_exp_f32_e32 v217, v14
	s_nop 0
	v_pk_add_f32 v[216:217], v[216:217], 1.0 op_sel_hi:[1,0]
	s_nop 0
	v_div_scale_f32 v14, s[2:3], v217, v217, v17
	v_rcp_f32_e32 v23, v14
	s_nop 0
	v_fma_f32 v218, -v14, v23, 1.0
	v_fmac_f32_e32 v23, v218, v23
	v_div_scale_f32 v218, vcc, v17, v217, v17
	v_mul_f32_e32 v219, v218, v23
	v_fma_f32 v224, -v14, v219, v218
	v_fmac_f32_e32 v219, v224, v23
	v_fma_f32 v14, -v14, v219, v218
	v_div_fmas_f32 v14, v14, v23, v219
	v_div_fixup_f32 v17, v14, v217, v17
	v_div_scale_f32 v14, s[2:3], v216, v216, v16
	v_rcp_f32_e32 v23, v14
	s_nop 0
	v_fma_f32 v217, -v14, v23, 1.0
	v_fmac_f32_e32 v23, v217, v23
	v_div_scale_f32 v217, vcc, v16, v216, v16
	v_mul_f32_e32 v218, v217, v23
	v_fma_f32 v219, -v14, v218, v217
	v_fmac_f32_e32 v218, v219, v23
	v_fma_f32 v14, -v14, v218, v217
	v_div_fmas_f32 v14, v14, v23, v218
	v_div_fixup_f32 v16, v14, v216, v16
	v_mov_b32_e32 v14, v93
	v_pk_mul_f32 v[14:15], v[14:15], v[28:29]
	s_nop 0
	v_pk_fma_f32 v[14:15], v[28:29], v[92:93], v[14:15] op_sel:[0,0,1] op_sel_hi:[1,0,0]
	v_pk_mov_b32 v[92:93], v[92:93], v[30:31] op_sel:[1,0]
	s_nop 0
	v_pk_fma_f32 v[14:15], v[22:23], v[92:93], v[14:15] op_sel_hi:[0,1,1]
	v_pk_fma_f32 v[14:15], v[24:25], v[30:31], v[14:15] op_sel_hi:[0,1,1]
	v_pk_add_f32 v[14:15], v[26:27], v[14:15] op_sel_hi:[0,1]
	v_mul_f32_e32 v23, 0xbfb8aa3b, v14
	v_exp_f32_e32 v216, v23
	v_mul_f32_e32 v23, 0xbfb8aa3b, v15
	v_exp_f32_e32 v217, v23
	s_nop 0
	v_pk_add_f32 v[216:217], v[216:217], 1.0 op_sel_hi:[1,0]
	s_nop 0
	v_div_scale_f32 v23, s[2:3], v217, v217, v15
	v_rcp_f32_e32 v218, v23
	s_nop 0
	v_fma_f32 v219, -v23, v218, 1.0
	v_fmac_f32_e32 v218, v219, v218
	v_div_scale_f32 v219, vcc, v15, v217, v15
	v_mul_f32_e32 v224, v219, v218
	v_fma_f32 v225, -v23, v224, v219
	v_fmac_f32_e32 v224, v225, v218
	v_fma_f32 v23, -v23, v224, v219
	v_div_fmas_f32 v23, v23, v218, v224
	v_div_fixup_f32 v15, v23, v217, v15
	v_div_scale_f32 v23, s[2:3], v216, v216, v14
	v_rcp_f32_e32 v217, v23
	s_nop 0
	v_fma_f32 v218, -v23, v217, 1.0
	v_fmac_f32_e32 v217, v218, v217
	v_div_scale_f32 v218, vcc, v14, v216, v14
	v_mul_f32_e32 v219, v218, v217
	v_fma_f32 v224, -v23, v219, v218
	v_fmac_f32_e32 v219, v224, v217
	v_fma_f32 v23, -v23, v219, v218
	v_div_fmas_f32 v23, v23, v217, v219
	v_pk_mul_f32 v[218:219], v[28:29], v[30:31] op_sel_hi:[0,1]
	v_div_fixup_f32 v14, v23, v216, v14
	v_lshlrev_b32_e32 v217, 16, v32
	v_lshlrev_b32_e32 v32, 16, v90
	v_pk_fma_f32 v[92:93], v[6:7], v[92:93], v[218:219] op_sel_hi:[0,1,1]
	v_mov_b32_e32 v216, v31
	v_pk_fma_f32 v[92:93], v[22:23], v[216:217], v[92:93] op_sel_hi:[0,1,1]
	v_mov_b32_e32 v218, v217
	v_mov_b32_e32 v219, v32
	v_pk_fma_f32 v[92:93], v[24:25], v[218:219], v[92:93] op_sel_hi:[0,1,1]
	v_pk_add_f32 v[92:93], v[26:27], v[92:93] op_sel_hi:[0,1]
	v_mul_f32_e32 v6, 0xbfb8aa3b, v92
	v_exp_f32_e32 v218, v6
	v_mul_f32_e32 v6, 0xbfb8aa3b, v93
	v_exp_f32_e32 v219, v6
	v_mov_b32_e32 v90, v33
	v_pk_add_f32 v[218:219], v[218:219], 1.0 op_sel_hi:[1,0]
	s_nop 0
	v_div_scale_f32 v6, s[2:3], v219, v219, v93
	v_rcp_f32_e32 v23, v6
	s_nop 0
	v_fma_f32 v30, -v6, v23, 1.0
	v_fmac_f32_e32 v23, v30, v23
	v_div_scale_f32 v30, vcc, v93, v219, v93
	v_mul_f32_e32 v216, v30, v23
	v_fma_f32 v224, -v6, v216, v30
	v_fmac_f32_e32 v216, v224, v23
	v_fma_f32 v6, -v6, v216, v30
	v_div_fmas_f32 v6, v6, v23, v216
	v_div_fixup_f32 v93, v6, v219, v93
	v_div_scale_f32 v6, s[2:3], v218, v218, v92
	v_rcp_f32_e32 v23, v6
	s_nop 0
	v_fma_f32 v30, -v6, v23, 1.0
	v_fmac_f32_e32 v23, v30, v23
	v_div_scale_f32 v30, vcc, v92, v218, v92
	v_mul_f32_e32 v216, v30, v23
	v_fma_f32 v219, -v6, v216, v30
	v_fmac_f32_e32 v216, v219, v23
	v_fma_f32 v6, -v6, v216, v30
	v_div_fmas_f32 v6, v6, v23, v216
	v_mov_b32_e32 v30, v32
	v_div_fixup_f32 v92, v6, v218, v92
	v_mov_b32_e32 v6, v217
	v_pk_mul_f32 v[30:31], v[28:29], v[30:31]
	s_nop 0
	v_pk_fma_f32 v[30:31], v[28:29], v[6:7], v[30:31] op_sel:[0,0,1] op_sel_hi:[1,0,0]
	s_nop 0
	v_pk_fma_f32 v[30:31], v[22:23], v[32:33], v[30:31] op_sel_hi:[0,1,1]
	v_pk_fma_f32 v[30:31], v[24:25], v[90:91], v[30:31] op_sel_hi:[0,1,1]
	v_pk_add_f32 v[30:31], v[26:27], v[30:31] op_sel_hi:[0,1]
	v_mul_f32_e32 v6, 0xbfb8aa3b, v30
	v_exp_f32_e32 v216, v6
	v_mul_f32_e32 v6, 0xbfb8aa3b, v31
	v_exp_f32_e32 v217, v6
	s_nop 0
	v_pk_add_f32 v[216:217], v[216:217], 1.0 op_sel_hi:[1,0]
	s_nop 0
	v_div_scale_f32 v6, s[2:3], v217, v217, v31
	v_rcp_f32_e32 v23, v6
	s_nop 0
	v_fma_f32 v218, -v6, v23, 1.0
	v_fmac_f32_e32 v23, v218, v23
	v_div_scale_f32 v218, vcc, v31, v217, v31
	v_mul_f32_e32 v219, v218, v23
	v_fma_f32 v224, -v6, v219, v218
	v_fmac_f32_e32 v219, v224, v23
	v_fma_f32 v6, -v6, v219, v218
	v_div_fmas_f32 v6, v6, v23, v219
	v_div_fixup_f32 v31, v6, v217, v31
	v_div_scale_f32 v6, s[2:3], v216, v216, v30
	v_rcp_f32_e32 v23, v6
	s_movk_i32 s2, 0x2200
	v_fma_f32 v217, -v6, v23, 1.0
	v_fmac_f32_e32 v23, v217, v23
	v_div_scale_f32 v217, vcc, v30, v216, v30
	v_mul_f32_e32 v218, v217, v23
	v_fma_f32 v219, -v6, v218, v217
	v_fmac_f32_e32 v218, v219, v23
	v_fma_f32 v6, -v6, v218, v217
	v_div_fmas_f32 v6, v6, v23, v218
	v_div_fixup_f32 v30, v6, v216, v30
	v_mad_i32_i24 v217, v25, s2, v0
	s_and_saveexec_b64 s[2:3], s[38:39]
	s_xor_b64 s[2:3], exec, s[2:3]
	s_cbranch_execz .LBB0_196
	v_cvt_pk_bf16_f32 v6, v16, s0
	ds_write_b16 v217, v6
	v_cvt_pk_bf16_f32 v6, v17, s0
	ds_write_b16 v217, v6 offset:272
	v_cvt_pk_bf16_f32 v6, v14, s0
	ds_write_b16 v217, v6 offset:544
	v_cvt_pk_bf16_f32 v6, v15, s0
	ds_write_b16 v217, v6 offset:816
	v_cvt_pk_bf16_f32 v6, v92, s0
	ds_write_b16 v217, v6 offset:1088
	v_cvt_pk_bf16_f32 v6, v93, s0
	ds_write_b16 v217, v6 offset:1360
	v_cvt_pk_bf16_f32 v6, v30, s0
	ds_write_b16 v217, v6 offset:1632
	v_cvt_pk_bf16_f32 v6, v31, s0
	ds_write_b16 v217, v6 offset:1904
